# adds P9 fused-epilogue stage A: per-row ssq3 atomics deferred to after last row (waits no longer drain an atomic per row)
# baseline (speedup 1.0000x reference)
.LBB0_1450:
	v_mov_b32_e32 v171, v191
	v_mov_b32_e32 v200, v190
	s_lshl_b32 s36, s67, 8
	v_add_u32_e32 v170, s52, v200
	v_add_u32_e32 v142, s36, v170
	v_ashrrev_i32_e32 v143, 31, v142
	v_lshl_add_u64 v[144:145], v[142:143], 2, s[12:13]
	flat_load_dword v162, v[144:145]
	v_lshl_add_u32 v140, v171, 3, s53
	v_ashrrev_i32_e32 v141, 31, v140
	v_lshlrev_b64 v[144:145], 12, v[142:143]
	v_lshl_add_u64 v[144:145], s[16:17], 0, v[144:145]
	v_lshlrev_b64 v[148:149], 1, v[140:141]
	v_ashrrev_i32_e32 v154, 8, v142
	v_lshl_add_u64 v[150:151], v[144:145], 0, v[148:149]
	v_ashrrev_i32_e32 v155, 31, v154
	global_load_dwordx4 v[144:147], v[150:151], off
	s_nop 0
	global_load_dwordx4 v[150:153], v[150:151], off offset:256
	v_lshlrev_b64 v[154:155], 21, v[154:155]
	v_lshlrev_b32_e32 v138, 12, v170
	v_lshl_add_u64 v[154:155], s[28:29], 0, v[154:155]
	v_and_b32_e32 v138, 0xff000, v138
	v_lshl_add_u64 v[154:155], v[154:155], 0, v[138:139]
	v_lshl_add_u64 v[158:159], v[154:155], 0, v[148:149]
	global_load_dwordx4 v[154:157], v[158:159], off
	s_nop 0
	global_load_dwordx4 v[158:161], v[158:159], off offset:256
	v_and_b32_e32 v163, 64, v197
	v_xor_b32_e32 v138, 16, v197
	v_add_u32_e32 v184, 64, v163
	v_cmp_lt_i32_e32 vcc, v138, v184
	s_waitcnt vmcnt(0)
	v_lshlrev_b32_e32 v164, 16, v146
	v_cndmask_b32_e32 v138, v197, v138, vcc
	v_lshlrev_b32_e32 v188, 2, v138
	s_waitcnt lgkmcnt(0)
	v_fmamk_f32 v138, v162, 0x3a000000, v198
	v_rsq_f32_e32 v138, v138
	v_lshlrev_b32_e32 v166, 16, v150
	v_and_b32_e32 v167, 0xffff0000, v150
	v_and_b32_e32 v165, 0xffff0000, v146
	v_mul_f32_e32 v138, 0xbfb8aa3b, v138
	v_mul_f32_e32 v118, v118, v138
	v_mul_f32_e32 v119, v119, v138
	v_mul_f32_e32 v116, v116, v138
	v_mul_f32_e32 v128, v128, v138
	v_mul_f32_e32 v129, v129, v138
	v_exp_f32_e32 v118, v118
	v_exp_f32_e32 v119, v119
	v_exp_f32_e32 v116, v116
	v_exp_f32_e32 v128, v128
	v_exp_f32_e32 v150, v129
	v_mul_f32_e32 v126, v126, v138
	v_mul_f32_e32 v127, v127, v138
	v_mul_f32_e32 v114, v114, v138
	v_mul_f32_e32 v115, v115, v138
	v_exp_f32_e32 v126, v126
	v_exp_f32_e32 v127, v127
	v_exp_f32_e32 v114, v114
	v_exp_f32_e32 v115, v115
	v_add_f32_e32 v129, 1.0, v118
	v_add_f32_e32 v146, 1.0, v119
	v_add_f32_e32 v116, 1.0, v116
	v_lshlrev_b32_e32 v172, 16, v154
	v_and_b32_e32 v173, 0xffff0000, v154
	v_add_f32_e32 v154, 1.0, v128
	v_rcp_f32_e32 v128, v129
	v_rcp_f32_e32 v129, v146
	v_rcp_f32_e32 v146, v116
	v_add_f32_e32 v116, 1.0, v150
	v_rcp_f32_e32 v183, v116
	v_mul_f32_e32 v116, v125, v138
	v_add_f32_e32 v126, 1.0, v126
	v_add_f32_e32 v127, 1.0, v127
	v_exp_f32_e32 v116, v116
	v_lshlrev_b32_e32 v162, 16, v144
	v_and_b32_e32 v163, 0xffff0000, v144
	v_lshlrev_b32_e32 v168, 16, v152
	v_and_b32_e32 v169, 0xffff0000, v152
	v_mul_f32_e32 v122, v122, v138
	v_mul_f32_e32 v123, v123, v138
	v_add_f32_e32 v144, 1.0, v114
	v_add_f32_e32 v152, 1.0, v115
	v_rcp_f32_e32 v114, v126
	v_rcp_f32_e32 v115, v127
	v_exp_f32_e32 v122, v122
	v_exp_f32_e32 v123, v123
	v_add_f32_e32 v116, 1.0, v116
	v_mul_f32_e32 v124, v124, v138
	v_pk_fma_f32 v[126:127], v[114:115], v[172:173], v[162:163]
	v_lshlrev_b32_e32 v162, 16, v145
	v_and_b32_e32 v163, 0xffff0000, v145
	v_rcp_f32_e32 v145, v116
	v_mul_f32_e32 v116, v121, v138
	v_mul_f32_e32 v120, v120, v138
	v_exp_f32_e32 v124, v124
	v_add_f32_e32 v122, 1.0, v122
	v_add_f32_e32 v123, 1.0, v123
	v_exp_f32_e32 v116, v116
	v_exp_f32_e32 v120, v120
	v_rcp_f32_e32 v118, v122
	v_rcp_f32_e32 v119, v123
	v_lshlrev_b32_e32 v174, 16, v156
	v_and_b32_e32 v175, 0xffff0000, v156
	v_lshlrev_b32_e32 v176, 16, v158
	v_and_b32_e32 v177, 0xffff0000, v158
	v_add_f32_e32 v124, 1.0, v124
	v_add_f32_e32 v116, 1.0, v116
	v_add_f32_e32 v120, 1.0, v120
	v_rcp_f32_e32 v180, v144
	v_rcp_f32_e32 v144, v124
	v_pk_fma_f32 v[122:123], v[118:119], v[174:175], v[164:165]
	v_pk_fma_f32 v[118:119], v[128:129], v[176:177], v[166:167]
	v_rcp_f32_e32 v129, v116
	v_mul_f32_e32 v116, v117, v138
	v_rcp_f32_e32 v128, v120
	v_exp_f32_e32 v138, v116
	v_rcp_f32_e32 v182, v154
	v_lshlrev_b32_e32 v124, 16, v155
	v_and_b32_e32 v125, 0xffff0000, v155
	v_lshlrev_b32_e32 v154, 16, v147
	v_and_b32_e32 v155, 0xffff0000, v147
	v_lshlrev_b32_e32 v120, 16, v157
	v_and_b32_e32 v121, 0xffff0000, v157
	v_pk_fma_f32 v[120:121], v[144:145], v[120:121], v[154:155]
	v_lshlrev_b32_e32 v144, 16, v151
	v_and_b32_e32 v145, 0xffff0000, v151
	v_lshlrev_b32_e32 v116, 16, v159
	v_and_b32_e32 v117, 0xffff0000, v159
	v_pk_fma_f32 v[116:117], v[128:129], v[116:117], v[144:145]
	v_add_f32_e32 v128, 1.0, v138
	v_rcp_f32_e32 v181, v152
	v_rcp_f32_e32 v147, v128
	v_lshlrev_b32_e32 v178, 16, v160
	v_and_b32_e32 v179, 0xffff0000, v160
	v_lshlrev_b32_e32 v128, 16, v153
	v_and_b32_e32 v129, 0xffff0000, v153
	v_lshlrev_b32_e32 v144, 16, v161
	v_and_b32_e32 v145, 0xffff0000, v161
	v_pk_fma_f32 v[114:115], v[180:181], v[178:179], v[168:169]
	v_pk_fma_f32 v[124:125], v[182:183], v[124:125], v[162:163]
	v_pk_fma_f32 v[128:129], v[146:147], v[144:145], v[128:129]
	v_pk_mul_f32 v[144:145], v[126:127], v[126:127]
	v_pk_mul_f32 v[146:147], v[124:125], v[124:125]
	v_pk_mul_f32 v[150:151], v[122:123], v[122:123]
	v_pk_mul_f32 v[152:153], v[120:121], v[120:121]
	v_pk_mul_f32 v[154:155], v[118:119], v[118:119]
	v_pk_mul_f32 v[156:157], v[116:117], v[116:117]
	v_pk_mul_f32 v[158:159], v[114:115], v[114:115]
	v_pk_mul_f32 v[160:161], v[128:129], v[128:129]
	v_add_f32_e32 v158, v158, v159
	v_add_f32_e32 v138, v160, v161
	v_add_f32_e32 v156, v156, v157
	v_add_f32_e32 v154, v154, v155
	v_add_f32_e32 v152, v152, v153
	v_add_f32_e32 v150, v150, v151
	v_add_f32_e32 v146, v146, v147
	v_add_f32_e32 v144, v144, v145
	v_add_f32_e32 v138, v158, v138
	v_add_f32_e32 v154, v154, v156
	v_add_f32_e32 v150, v150, v152
	v_add_f32_e32 v144, v144, v146
	v_add_f32_e32 v138, v154, v138
	v_add_f32_e32 v144, v144, v150
	v_add_f32_e32 v138, v144, v138
	ds_bpermute_b32 v144, v188, v138
	v_xor_b32_e32 v145, 32, v197
	v_cmp_lt_i32_e32 vcc, v145, v184
	v_lshl_add_u64 v[146:147], v[142:143], 2, s[14:15]
	s_waitcnt lgkmcnt(0)
	v_add_f32_e32 v138, v138, v144
	v_cndmask_b32_e32 v145, v197, v145, vcc
	v_lshlrev_b32_e32 v189, 2, v145
	ds_bpermute_b32 v144, v189, v138
	v_cmp_eq_u32_e32 vcc, 0, v171
	s_and_saveexec_b64 s[0:1], vcc
	s_cbranch_execz .LBB0_1452
	s_waitcnt lgkmcnt(0)
	v_add_f32_e32 v138, v138, v144
	v_mov_b32_e32 v224, v138
.LBB0_1452:
	s_or_b64 exec, exec, s[0:1]
	v_add_u32_e32 v138, 16, v170
	s_waitcnt lgkmcnt(0)
	v_add_u32_e32 v144, s36, v138
	v_ashrrev_i32_e32 v145, 31, v144
	v_lshl_add_u64 v[150:151], v[144:145], 2, s[12:13]
	flat_load_dword v166, v[150:151]
	v_lshlrev_b64 v[150:151], 12, v[144:145]
	v_lshl_add_u64 v[150:151], s[16:17], 0, v[150:151]
	v_lshl_add_u64 v[154:155], v[150:151], 0, v[148:149]
	v_ashrrev_i32_e32 v158, 8, v144
	global_load_dwordx4 v[150:153], v[154:155], off
	v_ashrrev_i32_e32 v159, 31, v158
	global_load_dwordx4 v[154:157], v[154:155], off offset:256
	v_lshlrev_b64 v[158:159], 21, v[158:159]
	v_lshlrev_b32_e32 v138, 12, v138
	v_lshl_add_u64 v[158:159], s[28:29], 0, v[158:159]
	v_and_b32_e32 v138, 0xff000, v138
	v_lshl_add_u64 v[158:159], v[158:159], 0, v[138:139]
	v_lshl_add_u64 v[162:163], v[158:159], 0, v[148:149]
	global_load_dwordx4 v[158:161], v[162:163], off
	s_nop 0
	global_load_dwordx4 v[162:165], v[162:163], off offset:256
	s_waitcnt vmcnt(0) lgkmcnt(0)
	v_fmamk_f32 v138, v166, 0x3a000000, v198
	v_rsq_f32_e32 v138, v138
	v_lshlrev_b32_e32 v168, 16, v152
	v_mul_f32_e32 v138, 0xbfb8aa3b, v138
	v_mul_f32_e32 v111, v111, v138
	v_mul_f32_e32 v103, v103, v138
	v_mul_f32_e32 v100, v100, v138
	v_mul_f32_e32 v99, v99, v138
	v_mul_f32_e32 v109, v109, v138
	v_exp_f32_e32 v111, v111
	v_exp_f32_e32 v103, v103
	v_exp_f32_e32 v100, v100
	v_lshlrev_b32_e32 v174, 16, v156
	v_and_b32_e32 v175, 0xffff0000, v156
	v_exp_f32_e32 v99, v99
	v_exp_f32_e32 v156, v109
	v_mul_f32_e32 v110, v110, v138
	v_mul_f32_e32 v98, v98, v138
	v_mul_f32_e32 v112, v112, v138
	v_mul_f32_e32 v113, v113, v138
	v_exp_f32_e32 v110, v110
	v_exp_f32_e32 v98, v98
	v_lshlrev_b32_e32 v172, 16, v154
	v_and_b32_e32 v173, 0xffff0000, v154
	v_exp_f32_e32 v112, v112
	v_exp_f32_e32 v113, v113
	v_add_f32_e32 v111, 1.0, v111
	v_add_f32_e32 v154, 1.0, v103
	v_add_f32_e32 v100, 1.0, v100
	v_lshlrev_b32_e32 v178, 16, v160
	v_and_b32_e32 v179, 0xffff0000, v160
	v_add_f32_e32 v160, 1.0, v99
	v_rcp_f32_e32 v99, v111
	v_rcp_f32_e32 v111, v154
	v_rcp_f32_e32 v154, v100
	v_add_f32_e32 v100, 1.0, v156
	v_mul_f32_e32 v108, v108, v138
	v_rcp_f32_e32 v187, v100
	v_mul_f32_e32 v100, v105, v138
	v_and_b32_e32 v169, 0xffff0000, v152
	v_mul_f32_e32 v104, v104, v138
	v_exp_f32_e32 v108, v108
	v_add_f32_e32 v109, 1.0, v110
	v_add_f32_e32 v152, 1.0, v98
	v_exp_f32_e32 v100, v100
	v_lshlrev_b32_e32 v180, 16, v162
	v_and_b32_e32 v181, 0xffff0000, v162
	v_lshlrev_b32_e32 v182, 16, v164
	v_and_b32_e32 v183, 0xffff0000, v164
	v_exp_f32_e32 v104, v104
	v_add_f32_e32 v162, 1.0, v112
	v_add_f32_e32 v164, 1.0, v113
	v_rcp_f32_e32 v98, v109
	v_rcp_f32_e32 v112, v152
	v_rcp_f32_e32 v113, v160
	v_lshlrev_b32_e32 v166, 16, v150
	v_and_b32_e32 v167, 0xffff0000, v150
	v_lshlrev_b32_e32 v176, 16, v158
	v_and_b32_e32 v177, 0xffff0000, v158
	v_mul_f32_e32 v106, v106, v138
	v_mul_f32_e32 v102, v102, v138
	v_mul_f32_e32 v107, v107, v138
	v_add_f32_e32 v108, 1.0, v108
	v_add_f32_e32 v100, 1.0, v100
	v_exp_f32_e32 v106, v106
	v_exp_f32_e32 v102, v102
	v_exp_f32_e32 v107, v107
	v_add_f32_e32 v104, 1.0, v104
	v_rcp_f32_e32 v186, v108
	v_pk_fma_f32 v[108:109], v[98:99], v[176:177], v[166:167]
	v_pk_fma_f32 v[98:99], v[112:113], v[182:183], v[174:175]
	v_lshlrev_b32_e32 v112, 16, v153
	v_and_b32_e32 v113, 0xffff0000, v153
	v_rcp_f32_e32 v153, v100
	v_mul_f32_e32 v100, v101, v138
	v_rcp_f32_e32 v152, v104
	v_exp_f32_e32 v138, v100
	v_lshlrev_b32_e32 v104, 16, v161
	v_and_b32_e32 v105, 0xffff0000, v161
	v_add_f32_e32 v106, 1.0, v106
	v_add_f32_e32 v110, 1.0, v102
	v_add_f32_e32 v107, 1.0, v107
	v_pk_fma_f32 v[104:105], v[186:187], v[104:105], v[112:113]
	v_lshlrev_b32_e32 v112, 16, v155
	v_and_b32_e32 v113, 0xffff0000, v155
	v_lshlrev_b32_e32 v100, 16, v163
	v_and_b32_e32 v101, 0xffff0000, v163
	v_rcp_f32_e32 v102, v106
	v_rcp_f32_e32 v110, v110
	v_rcp_f32_e32 v103, v107
	v_rcp_f32_e32 v184, v162
	v_rcp_f32_e32 v185, v164
	v_pk_fma_f32 v[100:101], v[152:153], v[100:101], v[112:113]
	v_add_f32_e32 v112, 1.0, v138
	v_rcp_f32_e32 v155, v112
	v_lshlrev_b32_e32 v150, 16, v151
	v_and_b32_e32 v151, 0xffff0000, v151
	v_lshlrev_b32_e32 v158, 16, v159
	v_and_b32_e32 v159, 0xffff0000, v159
	v_pk_fma_f32 v[106:107], v[102:103], v[178:179], v[168:169]
	v_pk_fma_f32 v[102:103], v[110:111], v[180:181], v[172:173]
	v_pk_fma_f32 v[110:111], v[184:185], v[158:159], v[150:151]
	v_lshlrev_b32_e32 v112, 16, v157
	v_and_b32_e32 v113, 0xffff0000, v157
	v_lshlrev_b32_e32 v150, 16, v165
	v_and_b32_e32 v151, 0xffff0000, v165
	v_pk_fma_f32 v[112:113], v[154:155], v[150:151], v[112:113]
	v_pk_mul_f32 v[150:151], v[108:109], v[108:109]
	v_pk_mul_f32 v[152:153], v[110:111], v[110:111]
	v_pk_mul_f32 v[154:155], v[106:107], v[106:107]
	v_pk_mul_f32 v[156:157], v[104:105], v[104:105]
	v_pk_mul_f32 v[158:159], v[102:103], v[102:103]
	v_pk_mul_f32 v[160:161], v[100:101], v[100:101]
	v_pk_mul_f32 v[162:163], v[98:99], v[98:99]
	v_pk_mul_f32 v[164:165], v[112:113], v[112:113]
	v_add_f32_e32 v162, v162, v163
	v_add_f32_e32 v138, v164, v165
	v_add_f32_e32 v160, v160, v161
	v_add_f32_e32 v158, v158, v159
	v_add_f32_e32 v156, v156, v157
	v_add_f32_e32 v154, v154, v155
	v_add_f32_e32 v152, v152, v153
	v_add_f32_e32 v150, v150, v151
	v_add_f32_e32 v138, v162, v138
	v_add_f32_e32 v158, v158, v160
	v_add_f32_e32 v154, v154, v156
	v_add_f32_e32 v150, v150, v152
	v_add_f32_e32 v138, v158, v138
	v_add_f32_e32 v150, v150, v154
	v_add_f32_e32 v138, v150, v138
	ds_bpermute_b32 v150, v188, v138
	v_lshl_add_u64 v[152:153], v[144:145], 2, s[14:15]
	s_waitcnt lgkmcnt(0)
	v_add_f32_e32 v138, v138, v150
	ds_bpermute_b32 v150, v189, v138
	s_and_saveexec_b64 s[0:1], vcc
	s_cbranch_execz .LBB0_1454
	s_waitcnt lgkmcnt(0)
	v_add_f32_e32 v138, v138, v150
	v_mov_b32_e32 v225, v138
.LBB0_1454:
	s_or_b64 exec, exec, s[0:1]
	v_add_u32_e32 v138, 32, v170
	s_waitcnt lgkmcnt(0)
	v_add_u32_e32 v150, s36, v138
	v_ashrrev_i32_e32 v151, 31, v150
	v_lshl_add_u64 v[154:155], v[150:151], 2, s[12:13]
	flat_load_dword v171, v[154:155]
	v_lshlrev_b64 v[154:155], 12, v[150:151]
	v_lshl_add_u64 v[154:155], s[16:17], 0, v[154:155]
	v_lshl_add_u64 v[158:159], v[154:155], 0, v[148:149]
	v_ashrrev_i32_e32 v162, 8, v150
	global_load_dwordx4 v[154:157], v[158:159], off
	v_ashrrev_i32_e32 v163, 31, v162
	global_load_dwordx4 v[158:161], v[158:159], off offset:256
	v_lshlrev_b64 v[162:163], 21, v[162:163]
	v_lshlrev_b32_e32 v138, 12, v138
	v_lshl_add_u64 v[162:163], s[28:29], 0, v[162:163]
	v_and_b32_e32 v138, 0xff000, v138
	v_lshl_add_u64 v[162:163], v[162:163], 0, v[138:139]
	v_lshl_add_u64 v[166:167], v[162:163], 0, v[148:149]
	global_load_dwordx4 v[162:165], v[166:167], off
	s_nop 0
	global_load_dwordx4 v[166:169], v[166:167], off offset:256
	s_waitcnt vmcnt(0) lgkmcnt(0)
	v_fmamk_f32 v138, v171, 0x3a000000, v198
	v_rsq_f32_e32 v138, v138
	v_lshlrev_b32_e32 v174, 16, v156
	v_mul_f32_e32 v138, 0xbfb8aa3b, v138
	v_mul_f32_e32 v95, v95, v138
	v_mul_f32_e32 v87, v87, v138
	v_mul_f32_e32 v84, v84, v138
	v_mul_f32_e32 v83, v83, v138
	v_mul_f32_e32 v93, v93, v138
	v_exp_f32_e32 v95, v95
	v_exp_f32_e32 v87, v87
	v_exp_f32_e32 v84, v84
	v_lshlrev_b32_e32 v178, 16, v160
	v_and_b32_e32 v179, 0xffff0000, v160
	v_exp_f32_e32 v83, v83
	v_exp_f32_e32 v160, v93
	v_mul_f32_e32 v94, v94, v138
	v_mul_f32_e32 v82, v82, v138
	v_mul_f32_e32 v96, v96, v138
	v_mul_f32_e32 v97, v97, v138
	v_exp_f32_e32 v94, v94
	v_exp_f32_e32 v82, v82
	v_lshlrev_b32_e32 v176, 16, v158
	v_and_b32_e32 v177, 0xffff0000, v158
	v_exp_f32_e32 v96, v96
	v_exp_f32_e32 v97, v97
	v_add_f32_e32 v95, 1.0, v95
	v_add_f32_e32 v158, 1.0, v87
	v_add_f32_e32 v84, 1.0, v84
	v_lshlrev_b32_e32 v182, 16, v164
	v_and_b32_e32 v183, 0xffff0000, v164
	v_add_f32_e32 v164, 1.0, v83
	v_rcp_f32_e32 v83, v95
	v_rcp_f32_e32 v95, v158
	v_rcp_f32_e32 v158, v84
	v_add_f32_e32 v84, 1.0, v160
	v_mul_f32_e32 v92, v92, v138
	v_rcp_f32_e32 v205, v84
	v_mul_f32_e32 v84, v89, v138
	v_and_b32_e32 v175, 0xffff0000, v156
	v_mul_f32_e32 v88, v88, v138
	v_exp_f32_e32 v92, v92
	v_add_f32_e32 v93, 1.0, v94
	v_add_f32_e32 v156, 1.0, v82
	v_exp_f32_e32 v84, v84
	v_lshlrev_b32_e32 v184, 16, v166
	v_and_b32_e32 v185, 0xffff0000, v166
	v_lshlrev_b32_e32 v186, 16, v168
	v_and_b32_e32 v187, 0xffff0000, v168
	v_exp_f32_e32 v88, v88
	v_add_f32_e32 v166, 1.0, v96
	v_add_f32_e32 v168, 1.0, v97
	v_rcp_f32_e32 v82, v93
	v_rcp_f32_e32 v96, v156
	v_rcp_f32_e32 v97, v164
	v_lshlrev_b32_e32 v172, 16, v154
	v_and_b32_e32 v173, 0xffff0000, v154
	v_lshlrev_b32_e32 v180, 16, v162
	v_and_b32_e32 v181, 0xffff0000, v162
	v_mul_f32_e32 v90, v90, v138
	v_mul_f32_e32 v86, v86, v138
	v_mul_f32_e32 v91, v91, v138
	v_add_f32_e32 v92, 1.0, v92
	v_add_f32_e32 v84, 1.0, v84
	v_exp_f32_e32 v90, v90
	v_exp_f32_e32 v86, v86
	v_exp_f32_e32 v91, v91
	v_add_f32_e32 v88, 1.0, v88
	v_rcp_f32_e32 v204, v92
	v_pk_fma_f32 v[92:93], v[82:83], v[180:181], v[172:173]
	v_pk_fma_f32 v[82:83], v[96:97], v[186:187], v[178:179]
	v_lshlrev_b32_e32 v96, 16, v157
	v_and_b32_e32 v97, 0xffff0000, v157
	v_rcp_f32_e32 v157, v84
	v_mul_f32_e32 v84, v85, v138
	v_rcp_f32_e32 v156, v88
	v_exp_f32_e32 v138, v84
	v_lshlrev_b32_e32 v88, 16, v165
	v_and_b32_e32 v89, 0xffff0000, v165
	v_add_f32_e32 v90, 1.0, v90
	v_add_f32_e32 v94, 1.0, v86
	v_add_f32_e32 v91, 1.0, v91
	v_pk_fma_f32 v[88:89], v[204:205], v[88:89], v[96:97]
	v_lshlrev_b32_e32 v96, 16, v159
	v_and_b32_e32 v97, 0xffff0000, v159
	v_lshlrev_b32_e32 v84, 16, v167
	v_and_b32_e32 v85, 0xffff0000, v167
	v_rcp_f32_e32 v86, v90
	v_rcp_f32_e32 v94, v94
	v_rcp_f32_e32 v87, v91
	v_rcp_f32_e32 v202, v166
	v_rcp_f32_e32 v203, v168
	v_pk_fma_f32 v[84:85], v[156:157], v[84:85], v[96:97]
	v_add_f32_e32 v96, 1.0, v138
	v_rcp_f32_e32 v159, v96
	v_lshlrev_b32_e32 v154, 16, v155
	v_and_b32_e32 v155, 0xffff0000, v155
	v_lshlrev_b32_e32 v162, 16, v163
	v_and_b32_e32 v163, 0xffff0000, v163
	v_pk_fma_f32 v[90:91], v[86:87], v[182:183], v[174:175]
	v_pk_fma_f32 v[86:87], v[94:95], v[184:185], v[176:177]
	v_pk_fma_f32 v[94:95], v[202:203], v[162:163], v[154:155]
	v_lshlrev_b32_e32 v96, 16, v161
	v_and_b32_e32 v97, 0xffff0000, v161
	v_lshlrev_b32_e32 v154, 16, v169
	v_and_b32_e32 v155, 0xffff0000, v169
	v_pk_fma_f32 v[96:97], v[158:159], v[154:155], v[96:97]
	v_pk_mul_f32 v[154:155], v[92:93], v[92:93]
	v_pk_mul_f32 v[156:157], v[94:95], v[94:95]
	v_pk_mul_f32 v[158:159], v[90:91], v[90:91]
	v_pk_mul_f32 v[160:161], v[88:89], v[88:89]
	v_pk_mul_f32 v[162:163], v[86:87], v[86:87]
	v_pk_mul_f32 v[164:165], v[84:85], v[84:85]
	v_pk_mul_f32 v[166:167], v[82:83], v[82:83]
	v_pk_mul_f32 v[168:169], v[96:97], v[96:97]
	v_add_f32_e32 v166, v166, v167
	v_add_f32_e32 v138, v168, v169
	v_add_f32_e32 v164, v164, v165
	v_add_f32_e32 v162, v162, v163
	v_add_f32_e32 v160, v160, v161
	v_add_f32_e32 v158, v158, v159
	v_add_f32_e32 v156, v156, v157
	v_add_f32_e32 v154, v154, v155
	v_add_f32_e32 v138, v166, v138
	v_add_f32_e32 v162, v162, v164
	v_add_f32_e32 v158, v158, v160
	v_add_f32_e32 v154, v154, v156
	v_add_f32_e32 v138, v162, v138
	v_add_f32_e32 v154, v154, v158
	v_add_f32_e32 v138, v154, v138
	ds_bpermute_b32 v154, v188, v138
	v_lshl_add_u64 v[156:157], v[150:151], 2, s[14:15]
	s_waitcnt lgkmcnt(0)
	v_add_f32_e32 v138, v138, v154
	ds_bpermute_b32 v154, v189, v138
	s_and_saveexec_b64 s[0:1], vcc
	s_cbranch_execz .LBB0_1456
	s_waitcnt lgkmcnt(0)
	v_add_f32_e32 v138, v138, v154
	v_mov_b32_e32 v226, v138
.LBB0_1456:
	s_or_b64 exec, exec, s[0:1]
	v_add_u32_e32 v138, 48, v170
	s_waitcnt lgkmcnt(0)
	v_add_u32_e32 v154, s36, v138
	v_ashrrev_i32_e32 v155, 31, v154
	v_lshl_add_u64 v[158:159], v[154:155], 2, s[12:13]
	flat_load_dword v171, v[158:159]
	v_lshlrev_b64 v[158:159], 12, v[154:155]
	v_lshl_add_u64 v[158:159], s[16:17], 0, v[158:159]
	v_lshl_add_u64 v[162:163], v[158:159], 0, v[148:149]
	v_ashrrev_i32_e32 v166, 8, v154
	global_load_dwordx4 v[158:161], v[162:163], off
	v_ashrrev_i32_e32 v167, 31, v166
	global_load_dwordx4 v[162:165], v[162:163], off offset:256
	v_lshlrev_b64 v[166:167], 21, v[166:167]
	v_lshlrev_b32_e32 v138, 12, v138
	v_lshl_add_u64 v[166:167], s[28:29], 0, v[166:167]
	v_and_b32_e32 v138, 0xff000, v138
	v_lshl_add_u64 v[166:167], v[166:167], 0, v[138:139]
	v_lshl_add_u64 v[172:173], v[166:167], 0, v[148:149]
	global_load_dwordx4 v[166:169], v[172:173], off
	s_nop 0
	global_load_dwordx4 v[172:175], v[172:173], off offset:256
	s_waitcnt vmcnt(0) lgkmcnt(0)
	v_fmamk_f32 v138, v171, 0x3a000000, v198
	v_rsq_f32_e32 v138, v138
	v_lshlrev_b32_e32 v178, 16, v160
	v_mul_f32_e32 v138, 0xbfb8aa3b, v138
	v_mul_f32_e32 v79, v79, v138
	v_mul_f32_e32 v71, v71, v138
	v_mul_f32_e32 v68, v68, v138
	v_mul_f32_e32 v67, v67, v138
	v_mul_f32_e32 v77, v77, v138
	v_exp_f32_e32 v79, v79
	v_exp_f32_e32 v71, v71
	v_exp_f32_e32 v68, v68
	v_lshlrev_b32_e32 v182, 16, v164
	v_and_b32_e32 v183, 0xffff0000, v164
	v_exp_f32_e32 v67, v67
	v_exp_f32_e32 v164, v77
	v_mul_f32_e32 v78, v78, v138
	v_mul_f32_e32 v66, v66, v138
	v_mul_f32_e32 v80, v80, v138
	v_mul_f32_e32 v81, v81, v138
	v_exp_f32_e32 v78, v78
	v_exp_f32_e32 v66, v66
	v_lshlrev_b32_e32 v180, 16, v162
	v_and_b32_e32 v181, 0xffff0000, v162
	v_exp_f32_e32 v80, v80
	v_exp_f32_e32 v81, v81
	v_add_f32_e32 v79, 1.0, v79
	v_add_f32_e32 v162, 1.0, v71
	v_add_f32_e32 v68, 1.0, v68
	v_lshlrev_b32_e32 v186, 16, v168
	v_and_b32_e32 v187, 0xffff0000, v168
	v_add_f32_e32 v168, 1.0, v67
	v_rcp_f32_e32 v67, v79
	v_rcp_f32_e32 v79, v162
	v_rcp_f32_e32 v162, v68
	v_add_f32_e32 v68, 1.0, v164
	v_mul_f32_e32 v76, v76, v138
	v_rcp_f32_e32 v211, v68
	v_mul_f32_e32 v68, v73, v138
	v_and_b32_e32 v179, 0xffff0000, v160
	v_mul_f32_e32 v72, v72, v138
	v_exp_f32_e32 v76, v76
	v_add_f32_e32 v77, 1.0, v78
	v_add_f32_e32 v160, 1.0, v66
	v_exp_f32_e32 v68, v68
	v_lshlrev_b32_e32 v202, 16, v172
	v_and_b32_e32 v203, 0xffff0000, v172
	v_exp_f32_e32 v72, v72
	v_add_f32_e32 v171, 1.0, v80
	v_add_f32_e32 v172, 1.0, v81
	v_rcp_f32_e32 v66, v77
	v_rcp_f32_e32 v80, v160
	v_rcp_f32_e32 v81, v168
	v_lshlrev_b32_e32 v176, 16, v158
	v_and_b32_e32 v177, 0xffff0000, v158
	v_lshlrev_b32_e32 v184, 16, v166
	v_and_b32_e32 v185, 0xffff0000, v166
	v_lshlrev_b32_e32 v204, 16, v174
	v_and_b32_e32 v205, 0xffff0000, v174
	v_mul_f32_e32 v74, v74, v138
	v_mul_f32_e32 v70, v70, v138
	v_mul_f32_e32 v75, v75, v138
	v_add_f32_e32 v76, 1.0, v76
	v_add_f32_e32 v68, 1.0, v68
	v_exp_f32_e32 v74, v74
	v_exp_f32_e32 v70, v70
	v_exp_f32_e32 v75, v75
	v_add_f32_e32 v72, 1.0, v72
	v_rcp_f32_e32 v210, v76
	v_pk_fma_f32 v[76:77], v[66:67], v[184:185], v[176:177]
	v_pk_fma_f32 v[66:67], v[80:81], v[204:205], v[182:183]
	v_lshlrev_b32_e32 v80, 16, v161
	v_and_b32_e32 v81, 0xffff0000, v161
	v_rcp_f32_e32 v161, v68
	v_mul_f32_e32 v68, v69, v138
	v_rcp_f32_e32 v160, v72
	v_exp_f32_e32 v138, v68
	v_lshlrev_b32_e32 v72, 16, v169
	v_and_b32_e32 v73, 0xffff0000, v169
	v_add_f32_e32 v74, 1.0, v74
	v_add_f32_e32 v78, 1.0, v70
	v_add_f32_e32 v75, 1.0, v75
	v_pk_fma_f32 v[72:73], v[210:211], v[72:73], v[80:81]
	v_lshlrev_b32_e32 v80, 16, v163
	v_and_b32_e32 v81, 0xffff0000, v163
	v_lshlrev_b32_e32 v68, 16, v173
	v_and_b32_e32 v69, 0xffff0000, v173
	v_rcp_f32_e32 v70, v74
	v_rcp_f32_e32 v78, v78
	v_rcp_f32_e32 v71, v75
	v_rcp_f32_e32 v206, v171
	v_rcp_f32_e32 v207, v172
	v_pk_fma_f32 v[68:69], v[160:161], v[68:69], v[80:81]
	v_add_f32_e32 v80, 1.0, v138
	v_rcp_f32_e32 v163, v80
	v_lshlrev_b32_e32 v158, 16, v159
	v_and_b32_e32 v159, 0xffff0000, v159
	v_lshlrev_b32_e32 v166, 16, v167
	v_and_b32_e32 v167, 0xffff0000, v167
	v_pk_fma_f32 v[74:75], v[70:71], v[186:187], v[178:179]
	v_pk_fma_f32 v[70:71], v[78:79], v[202:203], v[180:181]
	v_pk_fma_f32 v[78:79], v[206:207], v[166:167], v[158:159]
	v_lshlrev_b32_e32 v80, 16, v165
	v_and_b32_e32 v81, 0xffff0000, v165
	v_lshlrev_b32_e32 v158, 16, v175
	v_and_b32_e32 v159, 0xffff0000, v175
	v_pk_fma_f32 v[80:81], v[162:163], v[158:159], v[80:81]
	v_pk_mul_f32 v[158:159], v[76:77], v[76:77]
	v_pk_mul_f32 v[160:161], v[78:79], v[78:79]
	v_pk_mul_f32 v[162:163], v[74:75], v[74:75]
	v_pk_mul_f32 v[164:165], v[72:73], v[72:73]
	v_pk_mul_f32 v[166:167], v[70:71], v[70:71]
	v_pk_mul_f32 v[168:169], v[68:69], v[68:69]
	v_pk_mul_f32 v[172:173], v[66:67], v[66:67]
	v_pk_mul_f32 v[174:175], v[80:81], v[80:81]
	v_add_f32_e32 v171, v172, v173
	v_add_f32_e32 v138, v174, v175
	v_add_f32_e32 v168, v168, v169
	v_add_f32_e32 v166, v166, v167
	v_add_f32_e32 v164, v164, v165
	v_add_f32_e32 v162, v162, v163
	v_add_f32_e32 v160, v160, v161
	v_add_f32_e32 v158, v158, v159
	v_add_f32_e32 v138, v171, v138
	v_add_f32_e32 v166, v166, v168
	v_add_f32_e32 v162, v162, v164
	v_add_f32_e32 v158, v158, v160
	v_add_f32_e32 v138, v166, v138
	v_add_f32_e32 v158, v158, v162
	v_add_f32_e32 v138, v158, v138
	ds_bpermute_b32 v158, v188, v138
	v_lshl_add_u64 v[160:161], v[154:155], 2, s[14:15]
	s_waitcnt lgkmcnt(0)
	v_add_f32_e32 v138, v138, v158
	ds_bpermute_b32 v158, v189, v138
	s_and_saveexec_b64 s[0:1], vcc
	s_cbranch_execz .LBB0_1458
	s_waitcnt lgkmcnt(0)
	v_add_f32_e32 v138, v138, v158
	v_mov_b32_e32 v227, v138
.LBB0_1458:
	s_or_b64 exec, exec, s[0:1]
	v_add_u32_e32 v138, 0x80, v170
	s_waitcnt lgkmcnt(0)
	v_add_u32_e32 v158, s36, v138
	v_ashrrev_i32_e32 v159, 31, v158
	v_lshl_add_u64 v[162:163], v[158:159], 2, s[12:13]
	flat_load_dword v171, v[162:163]
	v_lshlrev_b64 v[162:163], 12, v[158:159]
	v_lshl_add_u64 v[162:163], s[16:17], 0, v[162:163]
	v_lshl_add_u64 v[166:167], v[162:163], 0, v[148:149]
	global_load_dwordx4 v[162:165], v[166:167], off
	v_ashrrev_i32_e32 v172, 8, v158
	global_load_dwordx4 v[166:169], v[166:167], off offset:256
	v_ashrrev_i32_e32 v173, 31, v172
	v_lshlrev_b64 v[172:173], 21, v[172:173]
	v_lshlrev_b32_e32 v138, 12, v138
	v_lshl_add_u64 v[172:173], s[28:29], 0, v[172:173]
	v_and_b32_e32 v138, 0xff000, v138
	v_lshl_add_u64 v[172:173], v[172:173], 0, v[138:139]
	v_lshl_add_u64 v[176:177], v[172:173], 0, v[148:149]
	global_load_dwordx4 v[172:175], v[176:177], off
	s_nop 0
	global_load_dwordx4 v[176:179], v[176:177], off offset:256
	s_waitcnt vmcnt(0) lgkmcnt(0)
	v_fmamk_f32 v138, v171, 0x3a000000, v198
	v_rsq_f32_e32 v138, v138
	v_lshlrev_b32_e32 v182, 16, v164
	v_mul_f32_e32 v138, 0xbfb8aa3b, v138
	v_mul_f32_e32 v63, v63, v138
	v_mul_f32_e32 v55, v55, v138
	v_mul_f32_e32 v52, v52, v138
	v_mul_f32_e32 v51, v51, v138
	v_mul_f32_e32 v61, v61, v138
	v_exp_f32_e32 v63, v63
	v_exp_f32_e32 v55, v55
	v_exp_f32_e32 v52, v52
	v_lshlrev_b32_e32 v186, 16, v168
	v_and_b32_e32 v187, 0xffff0000, v168
	v_exp_f32_e32 v51, v51
	v_exp_f32_e32 v168, v61
	v_mul_f32_e32 v62, v62, v138
	v_mul_f32_e32 v50, v50, v138
	v_mul_f32_e32 v64, v64, v138
	v_mul_f32_e32 v65, v65, v138
	v_exp_f32_e32 v62, v62
	v_exp_f32_e32 v50, v50
	v_lshlrev_b32_e32 v184, 16, v166
	v_and_b32_e32 v185, 0xffff0000, v166
	v_exp_f32_e32 v64, v64
	v_exp_f32_e32 v65, v65
	v_add_f32_e32 v63, 1.0, v63
	v_add_f32_e32 v166, 1.0, v55
	v_add_f32_e32 v52, 1.0, v52
	v_add_f32_e32 v171, 1.0, v51
	v_rcp_f32_e32 v51, v63
	v_rcp_f32_e32 v63, v166
	v_rcp_f32_e32 v166, v52
	v_add_f32_e32 v52, 1.0, v168
	v_mul_f32_e32 v60, v60, v138
	v_rcp_f32_e32 v215, v52
	v_mul_f32_e32 v52, v57, v138
	v_and_b32_e32 v183, 0xffff0000, v164
	v_mul_f32_e32 v56, v56, v138
	v_exp_f32_e32 v60, v60
	v_add_f32_e32 v61, 1.0, v62
	v_add_f32_e32 v164, 1.0, v50
	v_exp_f32_e32 v52, v52
	v_lshlrev_b32_e32 v204, 16, v174
	v_and_b32_e32 v205, 0xffff0000, v174
	v_lshlrev_b32_e32 v206, 16, v176
	v_and_b32_e32 v207, 0xffff0000, v176
	v_exp_f32_e32 v56, v56
	v_add_f32_e32 v174, 1.0, v64
	v_add_f32_e32 v176, 1.0, v65
	v_rcp_f32_e32 v50, v61
	v_rcp_f32_e32 v64, v164
	v_rcp_f32_e32 v65, v171
	v_lshlrev_b32_e32 v180, 16, v162
	v_and_b32_e32 v181, 0xffff0000, v162
	v_lshlrev_b32_e32 v202, 16, v172
	v_and_b32_e32 v203, 0xffff0000, v172
	v_lshlrev_b32_e32 v210, 16, v178
	v_and_b32_e32 v211, 0xffff0000, v178
	v_mul_f32_e32 v58, v58, v138
	v_mul_f32_e32 v54, v54, v138
	v_mul_f32_e32 v59, v59, v138
	v_add_f32_e32 v60, 1.0, v60
	v_add_f32_e32 v52, 1.0, v52
	v_exp_f32_e32 v58, v58
	v_exp_f32_e32 v54, v54
	v_exp_f32_e32 v59, v59
	v_add_f32_e32 v56, 1.0, v56
	v_rcp_f32_e32 v214, v60
	v_pk_fma_f32 v[60:61], v[50:51], v[202:203], v[180:181]
	v_pk_fma_f32 v[50:51], v[64:65], v[210:211], v[186:187]
	v_lshlrev_b32_e32 v64, 16, v165
	v_and_b32_e32 v65, 0xffff0000, v165
	v_rcp_f32_e32 v165, v52
	v_mul_f32_e32 v52, v53, v138
	v_rcp_f32_e32 v164, v56
	v_exp_f32_e32 v138, v52
	v_lshlrev_b32_e32 v56, 16, v175
	v_and_b32_e32 v57, 0xffff0000, v175
	v_add_f32_e32 v58, 1.0, v58
	v_add_f32_e32 v62, 1.0, v54
	v_add_f32_e32 v59, 1.0, v59
	v_pk_fma_f32 v[56:57], v[214:215], v[56:57], v[64:65]
	v_lshlrev_b32_e32 v64, 16, v167
	v_and_b32_e32 v65, 0xffff0000, v167
	v_lshlrev_b32_e32 v52, 16, v177
	v_and_b32_e32 v53, 0xffff0000, v177
	v_rcp_f32_e32 v54, v58
	v_rcp_f32_e32 v62, v62
	v_rcp_f32_e32 v55, v59
	v_rcp_f32_e32 v212, v174
	v_rcp_f32_e32 v213, v176
	v_pk_fma_f32 v[52:53], v[164:165], v[52:53], v[64:65]
	v_add_f32_e32 v64, 1.0, v138
	v_rcp_f32_e32 v167, v64
	v_lshlrev_b32_e32 v162, 16, v163
	v_and_b32_e32 v163, 0xffff0000, v163
	v_lshlrev_b32_e32 v172, 16, v173
	v_and_b32_e32 v173, 0xffff0000, v173
	v_pk_fma_f32 v[58:59], v[54:55], v[204:205], v[182:183]
	v_pk_fma_f32 v[54:55], v[62:63], v[206:207], v[184:185]
	v_pk_fma_f32 v[62:63], v[212:213], v[172:173], v[162:163]
	v_lshlrev_b32_e32 v64, 16, v169
	v_and_b32_e32 v65, 0xffff0000, v169
	v_lshlrev_b32_e32 v162, 16, v179
	v_and_b32_e32 v163, 0xffff0000, v179
	v_pk_fma_f32 v[64:65], v[166:167], v[162:163], v[64:65]
	v_pk_mul_f32 v[176:177], v[50:51], v[50:51]
	v_pk_mul_f32 v[178:179], v[64:65], v[64:65]
	v_pk_mul_f32 v[162:163], v[60:61], v[60:61]
	v_pk_mul_f32 v[164:165], v[62:63], v[62:63]
	v_pk_mul_f32 v[166:167], v[58:59], v[58:59]
	v_pk_mul_f32 v[168:169], v[56:57], v[56:57]
	v_pk_mul_f32 v[172:173], v[54:55], v[54:55]
	v_pk_mul_f32 v[174:175], v[52:53], v[52:53]
	v_add_f32_e32 v138, v178, v179
	v_add_f32_e32 v171, v176, v177
	v_add_f32_e32 v138, v171, v138
	v_add_f32_e32 v171, v174, v175
	v_add_f32_e32 v172, v172, v173
	v_add_f32_e32 v168, v168, v169
	v_add_f32_e32 v166, v166, v167
	v_add_f32_e32 v164, v164, v165
	v_add_f32_e32 v162, v162, v163
	v_add_f32_e32 v171, v172, v171
	v_add_f32_e32 v166, v166, v168
	v_add_f32_e32 v162, v162, v164
	v_add_f32_e32 v138, v171, v138
	v_add_f32_e32 v162, v162, v166
	v_add_f32_e32 v138, v162, v138
	ds_bpermute_b32 v162, v188, v138
	v_lshl_add_u64 v[164:165], v[158:159], 2, s[14:15]
	s_waitcnt lgkmcnt(0)
	v_add_f32_e32 v138, v138, v162
	ds_bpermute_b32 v162, v189, v138
	s_and_saveexec_b64 s[0:1], vcc
	s_cbranch_execz .LBB0_1460
	s_waitcnt lgkmcnt(0)
	v_add_f32_e32 v138, v138, v162
	v_mov_b32_e32 v228, v138
.LBB0_1460:
	s_or_b64 exec, exec, s[0:1]
	v_add_u32_e32 v138, 0x90, v170
	s_waitcnt lgkmcnt(0)
	v_add_u32_e32 v162, s36, v138
	v_ashrrev_i32_e32 v163, 31, v162
	v_lshl_add_u64 v[166:167], v[162:163], 2, s[12:13]
	flat_load_dword v171, v[166:167]
	v_lshlrev_b64 v[166:167], 12, v[162:163]
	v_lshl_add_u64 v[166:167], s[16:17], 0, v[166:167]
	v_ashrrev_i32_e32 v176, 8, v162
	v_lshl_add_u64 v[172:173], v[166:167], 0, v[148:149]
	v_ashrrev_i32_e32 v177, 31, v176
	global_load_dwordx4 v[166:169], v[172:173], off
	v_lshlrev_b64 v[176:177], 21, v[176:177]
	global_load_dwordx4 v[172:175], v[172:173], off offset:256
	v_lshlrev_b32_e32 v138, 12, v138
	v_lshl_add_u64 v[176:177], s[28:29], 0, v[176:177]
	v_and_b32_e32 v138, 0xff000, v138
	v_lshl_add_u64 v[176:177], v[176:177], 0, v[138:139]
	v_lshl_add_u64 v[180:181], v[176:177], 0, v[148:149]
	global_load_dwordx4 v[176:179], v[180:181], off
	s_nop 0
	global_load_dwordx4 v[180:183], v[180:181], off offset:256
	s_waitcnt vmcnt(0) lgkmcnt(0)
	v_fmamk_f32 v138, v171, 0x3a000000, v198
	v_rsq_f32_e32 v138, v138
	v_lshlrev_b32_e32 v186, 16, v168
	v_mul_f32_e32 v138, 0xbfb8aa3b, v138
	v_mul_f32_e32 v47, v47, v138
	v_mul_f32_e32 v39, v39, v138
	v_mul_f32_e32 v36, v36, v138
	v_mul_f32_e32 v35, v35, v138
	v_mul_f32_e32 v45, v45, v138
	v_exp_f32_e32 v47, v47
	v_exp_f32_e32 v39, v39
	v_exp_f32_e32 v36, v36
	v_exp_f32_e32 v35, v35
	v_exp_f32_e32 v171, v45
	v_mul_f32_e32 v46, v46, v138
	v_mul_f32_e32 v34, v34, v138
	v_mul_f32_e32 v48, v48, v138
	v_mul_f32_e32 v49, v49, v138
	v_exp_f32_e32 v46, v46
	v_exp_f32_e32 v34, v34
	v_lshlrev_b32_e32 v202, 16, v172
	v_and_b32_e32 v203, 0xffff0000, v172
	v_exp_f32_e32 v48, v48
	v_exp_f32_e32 v49, v49
	v_add_f32_e32 v47, 1.0, v47
	v_add_f32_e32 v172, 1.0, v39
	v_add_f32_e32 v36, 1.0, v36
	v_lshlrev_b32_e32 v204, 16, v174
	v_and_b32_e32 v205, 0xffff0000, v174
	v_add_f32_e32 v174, 1.0, v35
	v_rcp_f32_e32 v35, v47
	v_rcp_f32_e32 v47, v172
	v_rcp_f32_e32 v172, v36
	v_add_f32_e32 v36, 1.0, v171
	v_mul_f32_e32 v44, v44, v138
	v_rcp_f32_e32 v219, v36
	v_mul_f32_e32 v36, v41, v138
	v_and_b32_e32 v187, 0xffff0000, v168
	v_mul_f32_e32 v40, v40, v138
	v_exp_f32_e32 v44, v44
	v_add_f32_e32 v45, 1.0, v46
	v_add_f32_e32 v168, 1.0, v34
	v_exp_f32_e32 v36, v36
	v_lshlrev_b32_e32 v210, 16, v178
	v_and_b32_e32 v211, 0xffff0000, v178
	v_lshlrev_b32_e32 v212, 16, v180
	v_and_b32_e32 v213, 0xffff0000, v180
	v_exp_f32_e32 v40, v40
	v_add_f32_e32 v178, 1.0, v48
	v_add_f32_e32 v180, 1.0, v49
	v_rcp_f32_e32 v34, v45
	v_rcp_f32_e32 v48, v168
	v_rcp_f32_e32 v49, v174
	v_lshlrev_b32_e32 v184, 16, v166
	v_and_b32_e32 v185, 0xffff0000, v166
	v_lshlrev_b32_e32 v206, 16, v176
	v_and_b32_e32 v207, 0xffff0000, v176
	v_lshlrev_b32_e32 v214, 16, v182
	v_and_b32_e32 v215, 0xffff0000, v182
	v_mul_f32_e32 v42, v42, v138
	v_mul_f32_e32 v38, v38, v138
	v_mul_f32_e32 v43, v43, v138
	v_add_f32_e32 v44, 1.0, v44
	v_add_f32_e32 v36, 1.0, v36
	v_exp_f32_e32 v42, v42
	v_exp_f32_e32 v38, v38
	v_exp_f32_e32 v43, v43
	v_add_f32_e32 v40, 1.0, v40
	v_rcp_f32_e32 v218, v44
	v_pk_fma_f32 v[44:45], v[34:35], v[206:207], v[184:185]
	v_pk_fma_f32 v[34:35], v[48:49], v[214:215], v[204:205]
	v_lshlrev_b32_e32 v48, 16, v169
	v_and_b32_e32 v49, 0xffff0000, v169
	v_rcp_f32_e32 v169, v36
	v_mul_f32_e32 v36, v37, v138
	v_rcp_f32_e32 v168, v40
	v_exp_f32_e32 v138, v36
	v_lshlrev_b32_e32 v40, 16, v179
	v_and_b32_e32 v41, 0xffff0000, v179
	v_add_f32_e32 v42, 1.0, v42
	v_add_f32_e32 v46, 1.0, v38
	v_add_f32_e32 v43, 1.0, v43
	v_pk_fma_f32 v[40:41], v[218:219], v[40:41], v[48:49]
	v_lshlrev_b32_e32 v48, 16, v173
	v_and_b32_e32 v49, 0xffff0000, v173
	v_lshlrev_b32_e32 v36, 16, v181
	v_and_b32_e32 v37, 0xffff0000, v181
	v_rcp_f32_e32 v38, v42
	v_rcp_f32_e32 v46, v46
	v_rcp_f32_e32 v39, v43
	v_rcp_f32_e32 v216, v178
	v_rcp_f32_e32 v217, v180
	v_pk_fma_f32 v[36:37], v[168:169], v[36:37], v[48:49]
	v_add_f32_e32 v48, 1.0, v138
	v_rcp_f32_e32 v173, v48
	v_lshlrev_b32_e32 v166, 16, v167
	v_and_b32_e32 v167, 0xffff0000, v167
	v_lshlrev_b32_e32 v176, 16, v177
	v_and_b32_e32 v177, 0xffff0000, v177
	v_pk_fma_f32 v[42:43], v[38:39], v[210:211], v[186:187]
	v_pk_fma_f32 v[38:39], v[46:47], v[212:213], v[202:203]
	v_pk_fma_f32 v[46:47], v[216:217], v[176:177], v[166:167]
	v_lshlrev_b32_e32 v48, 16, v175
	v_and_b32_e32 v49, 0xffff0000, v175
	v_lshlrev_b32_e32 v166, 16, v183
	v_and_b32_e32 v167, 0xffff0000, v183
	v_pk_fma_f32 v[48:49], v[172:173], v[166:167], v[48:49]
	v_pk_mul_f32 v[180:181], v[34:35], v[34:35]
	v_pk_mul_f32 v[182:183], v[48:49], v[48:49]
	v_pk_mul_f32 v[176:177], v[38:39], v[38:39]
	v_pk_mul_f32 v[178:179], v[36:37], v[36:37]
	v_add_f32_e32 v138, v182, v183
	v_add_f32_e32 v171, v180, v181
	v_add_f32_e32 v138, v171, v138
	v_add_f32_e32 v171, v178, v179
	v_add_f32_e32 v176, v176, v177
	v_pk_mul_f32 v[166:167], v[44:45], v[44:45]
	v_pk_mul_f32 v[168:169], v[46:47], v[46:47]
	v_pk_mul_f32 v[172:173], v[42:43], v[42:43]
	v_pk_mul_f32 v[174:175], v[40:41], v[40:41]
	v_add_f32_e32 v171, v176, v171
	v_add_f32_e32 v138, v171, v138
	v_add_f32_e32 v171, v174, v175
	v_add_f32_e32 v172, v172, v173
	v_add_f32_e32 v168, v168, v169
	v_add_f32_e32 v166, v166, v167
	v_add_f32_e32 v171, v172, v171
	v_add_f32_e32 v166, v166, v168
	v_add_f32_e32 v166, v166, v171
	v_add_f32_e32 v138, v166, v138
	ds_bpermute_b32 v166, v188, v138
	v_lshl_add_u64 v[168:169], v[162:163], 2, s[14:15]
	s_waitcnt lgkmcnt(0)
	v_add_f32_e32 v138, v138, v166
	ds_bpermute_b32 v166, v189, v138
	s_and_saveexec_b64 s[0:1], vcc
	s_cbranch_execz .LBB0_1462
	s_waitcnt lgkmcnt(0)
	v_add_f32_e32 v138, v138, v166
	v_mov_b32_e32 v229, v138
.LBB0_1462:
	s_or_b64 exec, exec, s[0:1]
	v_add_u32_e32 v138, 0xa0, v170
	s_waitcnt lgkmcnt(0)
	v_add_u32_e32 v166, s36, v138
	v_ashrrev_i32_e32 v167, 31, v166
	v_lshl_add_u64 v[172:173], v[166:167], 2, s[12:13]
	flat_load_dword v171, v[172:173]
	v_lshlrev_b64 v[172:173], 12, v[166:167]
	v_lshl_add_u64 v[172:173], s[16:17], 0, v[172:173]
	v_ashrrev_i32_e32 v180, 8, v166
	v_lshl_add_u64 v[176:177], v[172:173], 0, v[148:149]
	v_ashrrev_i32_e32 v181, 31, v180
	global_load_dwordx4 v[172:175], v[176:177], off
	v_lshlrev_b64 v[180:181], 21, v[180:181]
	global_load_dwordx4 v[176:179], v[176:177], off offset:256
	v_lshlrev_b32_e32 v138, 12, v138
	v_lshl_add_u64 v[180:181], s[28:29], 0, v[180:181]
	v_and_b32_e32 v138, 0xff000, v138
	v_lshl_add_u64 v[180:181], v[180:181], 0, v[138:139]
	v_lshl_add_u64 v[184:185], v[180:181], 0, v[148:149]
	global_load_dwordx4 v[180:183], v[184:185], off
	s_nop 0
	global_load_dwordx4 v[184:187], v[184:185], off offset:256
	s_waitcnt vmcnt(0) lgkmcnt(0)
	v_fmamk_f32 v138, v171, 0x3a000000, v198
	v_rsq_f32_e32 v138, v138
	v_lshlrev_b32_e32 v204, 16, v174
	v_mul_f32_e32 v138, 0xbfb8aa3b, v138
	v_mul_f32_e32 v31, v31, v138
	v_mul_f32_e32 v23, v23, v138
	v_mul_f32_e32 v20, v20, v138
	v_mul_f32_e32 v19, v19, v138
	v_mul_f32_e32 v29, v29, v138
	v_exp_f32_e32 v31, v31
	v_exp_f32_e32 v23, v23
	v_exp_f32_e32 v20, v20
	v_exp_f32_e32 v19, v19
	v_exp_f32_e32 v171, v29
	v_mul_f32_e32 v30, v30, v138
	v_mul_f32_e32 v18, v18, v138
	v_mul_f32_e32 v32, v32, v138
	v_mul_f32_e32 v33, v33, v138
	v_exp_f32_e32 v30, v30
	v_exp_f32_e32 v18, v18
	v_lshlrev_b32_e32 v206, 16, v176
	v_and_b32_e32 v207, 0xffff0000, v176
	v_exp_f32_e32 v32, v32
	v_exp_f32_e32 v33, v33
	v_add_f32_e32 v31, 1.0, v31
	v_add_f32_e32 v176, 1.0, v23
	v_add_f32_e32 v20, 1.0, v20
	v_lshlrev_b32_e32 v210, 16, v178
	v_and_b32_e32 v211, 0xffff0000, v178
	v_add_f32_e32 v178, 1.0, v19
	v_rcp_f32_e32 v19, v31
	v_rcp_f32_e32 v31, v176
	v_rcp_f32_e32 v176, v20
	v_add_f32_e32 v20, 1.0, v171
	v_mul_f32_e32 v28, v28, v138
	v_rcp_f32_e32 v223, v20
	v_mul_f32_e32 v20, v25, v138
	v_and_b32_e32 v205, 0xffff0000, v174
	v_mul_f32_e32 v24, v24, v138
	v_exp_f32_e32 v28, v28
	v_add_f32_e32 v29, 1.0, v30
	v_add_f32_e32 v174, 1.0, v18
	v_exp_f32_e32 v20, v20
	v_lshlrev_b32_e32 v214, 16, v182
	v_and_b32_e32 v215, 0xffff0000, v182
	v_lshlrev_b32_e32 v216, 16, v184
	v_and_b32_e32 v217, 0xffff0000, v184
	v_exp_f32_e32 v24, v24
	v_add_f32_e32 v182, 1.0, v32
	v_add_f32_e32 v184, 1.0, v33
	v_rcp_f32_e32 v18, v29
	v_rcp_f32_e32 v32, v174
	v_rcp_f32_e32 v33, v178
	v_lshlrev_b32_e32 v202, 16, v172
	v_and_b32_e32 v203, 0xffff0000, v172
	v_lshlrev_b32_e32 v212, 16, v180
	v_and_b32_e32 v213, 0xffff0000, v180
	v_lshlrev_b32_e32 v218, 16, v186
	v_and_b32_e32 v219, 0xffff0000, v186
	v_mul_f32_e32 v26, v26, v138
	v_mul_f32_e32 v22, v22, v138
	v_mul_f32_e32 v27, v27, v138
	v_add_f32_e32 v28, 1.0, v28
	v_add_f32_e32 v20, 1.0, v20
	v_exp_f32_e32 v26, v26
	v_exp_f32_e32 v22, v22
	v_exp_f32_e32 v27, v27
	v_add_f32_e32 v24, 1.0, v24
	v_rcp_f32_e32 v222, v28
	v_pk_fma_f32 v[28:29], v[18:19], v[212:213], v[202:203]
	v_pk_fma_f32 v[18:19], v[32:33], v[218:219], v[210:211]
	v_lshlrev_b32_e32 v32, 16, v175
	v_and_b32_e32 v33, 0xffff0000, v175
	v_rcp_f32_e32 v175, v20
	v_mul_f32_e32 v20, v21, v138
	v_rcp_f32_e32 v174, v24
	v_exp_f32_e32 v138, v20
	v_lshlrev_b32_e32 v24, 16, v183
	v_and_b32_e32 v25, 0xffff0000, v183
	v_add_f32_e32 v26, 1.0, v26
	v_add_f32_e32 v30, 1.0, v22
	v_add_f32_e32 v27, 1.0, v27
	v_pk_fma_f32 v[24:25], v[222:223], v[24:25], v[32:33]
	v_lshlrev_b32_e32 v32, 16, v177
	v_and_b32_e32 v33, 0xffff0000, v177
	v_lshlrev_b32_e32 v20, 16, v185
	v_and_b32_e32 v21, 0xffff0000, v185
	v_rcp_f32_e32 v22, v26
	v_rcp_f32_e32 v30, v30
	v_rcp_f32_e32 v23, v27
	v_rcp_f32_e32 v220, v182
	v_rcp_f32_e32 v221, v184
	v_pk_fma_f32 v[20:21], v[174:175], v[20:21], v[32:33]
	v_add_f32_e32 v32, 1.0, v138
	v_rcp_f32_e32 v177, v32
	v_lshlrev_b32_e32 v172, 16, v173
	v_and_b32_e32 v173, 0xffff0000, v173
	v_lshlrev_b32_e32 v180, 16, v181
	v_and_b32_e32 v181, 0xffff0000, v181
	v_pk_fma_f32 v[26:27], v[22:23], v[214:215], v[204:205]
	v_pk_fma_f32 v[22:23], v[30:31], v[216:217], v[206:207]
	v_pk_fma_f32 v[30:31], v[220:221], v[180:181], v[172:173]
	v_lshlrev_b32_e32 v32, 16, v179
	v_and_b32_e32 v33, 0xffff0000, v179
	v_lshlrev_b32_e32 v172, 16, v187
	v_and_b32_e32 v173, 0xffff0000, v187
	v_pk_fma_f32 v[32:33], v[176:177], v[172:173], v[32:33]
	v_pk_mul_f32 v[184:185], v[18:19], v[18:19]
	v_pk_mul_f32 v[186:187], v[32:33], v[32:33]
	v_pk_mul_f32 v[180:181], v[22:23], v[22:23]
	v_pk_mul_f32 v[182:183], v[20:21], v[20:21]
	v_add_f32_e32 v138, v186, v187
	v_add_f32_e32 v171, v184, v185
	v_add_f32_e32 v138, v171, v138
	v_add_f32_e32 v171, v182, v183
	v_add_f32_e32 v180, v180, v181
	v_pk_mul_f32 v[172:173], v[28:29], v[28:29]
	v_pk_mul_f32 v[174:175], v[30:31], v[30:31]
	v_pk_mul_f32 v[176:177], v[26:27], v[26:27]
	v_pk_mul_f32 v[178:179], v[24:25], v[24:25]
	v_add_f32_e32 v171, v180, v171
	v_add_f32_e32 v138, v171, v138
	v_add_f32_e32 v171, v178, v179
	v_add_f32_e32 v176, v176, v177
	v_add_f32_e32 v174, v174, v175
	v_add_f32_e32 v172, v172, v173
	v_add_f32_e32 v171, v176, v171
	v_add_f32_e32 v172, v172, v174
	v_add_f32_e32 v171, v172, v171
	v_add_f32_e32 v138, v171, v138
	ds_bpermute_b32 v171, v188, v138
	v_lshl_add_u64 v[172:173], v[166:167], 2, s[14:15]
	s_waitcnt lgkmcnt(0)
	v_add_f32_e32 v138, v138, v171
	ds_bpermute_b32 v171, v189, v138
	s_and_saveexec_b64 s[0:1], vcc
	s_cbranch_execz .LBB0_1464
	s_waitcnt lgkmcnt(0)
	v_add_f32_e32 v138, v138, v171
	v_mov_b32_e32 v230, v138
.LBB0_1464:
	s_or_b64 exec, exec, s[0:1]
	v_add_u32_e32 v138, 0xb0, v170
	v_add_u32_e32 v170, s36, v138
	s_waitcnt lgkmcnt(0)
	v_ashrrev_i32_e32 v171, 31, v170
	v_lshl_add_u64 v[174:175], v[170:171], 2, s[12:13]
	flat_load_dword v178, v[174:175]
	v_lshlrev_b64 v[174:175], 12, v[170:171]
	v_lshl_add_u64 v[174:175], s[16:17], 0, v[174:175]
	v_lshl_add_u64 v[174:175], v[174:175], 0, v[148:149]
	v_ashrrev_i32_e32 v176, 8, v170
	global_load_dwordx4 v[180:183], v[174:175], off
	global_load_dwordx4 v[184:187], v[174:175], off offset:256
	v_ashrrev_i32_e32 v177, 31, v176
	v_lshlrev_b64 v[174:175], 21, v[176:177]
	v_lshlrev_b32_e32 v138, 12, v138
	v_lshl_add_u64 v[174:175], s[28:29], 0, v[174:175]
	v_and_b32_e32 v138, 0xff000, v138
	v_lshl_add_u64 v[174:175], v[174:175], 0, v[138:139]
	v_lshl_add_u64 v[148:149], v[174:175], 0, v[148:149]
	global_load_dwordx4 v[202:205], v[148:149], off
	global_load_dwordx4 v[210:213], v[148:149], off offset:256
	s_waitcnt vmcnt(0) lgkmcnt(0)
	v_fmamk_f32 v138, v178, 0x3a000000, v198
	v_rsq_f32_e32 v138, v138
	v_lshlrev_b32_e32 v174, 16, v182
	v_mul_f32_e32 v138, 0xbfb8aa3b, v138
	v_mul_f32_e32 v14, v14, v138
	v_mul_f32_e32 v10, v10, v138
	v_mul_f32_e32 v15, v15, v138
	v_mul_f32_e32 v11, v11, v138
	v_mul_f32_e32 v6, v6, v138
	v_mul_f32_e32 v2, v2, v138
	v_mul_f32_e32 v7, v7, v138
	v_mul_f32_e32 v3, v3, v138
	v_exp_f32_e32 v14, v14
	v_exp_f32_e32 v10, v10
	v_exp_f32_e32 v15, v15
	v_exp_f32_e32 v11, v11
	v_exp_f32_e32 v6, v6
	v_exp_f32_e32 v2, v2
	v_exp_f32_e32 v7, v7
	v_exp_f32_e32 v3, v3
	v_mul_f32_e32 v13, v13, v138
	v_and_b32_e32 v175, 0xffff0000, v182
	v_mul_f32_e32 v16, v16, v138
	v_mul_f32_e32 v12, v12, v138
	v_mul_f32_e32 v17, v17, v138
	v_exp_f32_e32 v182, v13
	v_add_f32_e32 v13, 1.0, v14
	v_add_f32_e32 v10, 1.0, v10
	v_add_f32_e32 v15, 1.0, v15
	v_add_f32_e32 v11, 1.0, v11
	v_lshlrev_b32_e32 v206, 16, v184
	v_and_b32_e32 v207, 0xffff0000, v184
	v_exp_f32_e32 v16, v16
	v_exp_f32_e32 v12, v12
	v_exp_f32_e32 v17, v17
	v_add_f32_e32 v14, 1.0, v6
	v_add_f32_e32 v178, 1.0, v2
	v_add_f32_e32 v179, 1.0, v7
	v_add_f32_e32 v184, 1.0, v3
	v_rcp_f32_e32 v2, v13
	v_rcp_f32_e32 v6, v10
	v_rcp_f32_e32 v3, v15
	v_rcp_f32_e32 v7, v11
	v_lshlrev_b32_e32 v148, 16, v180
	v_and_b32_e32 v149, 0xffff0000, v180
	v_lshlrev_b32_e32 v176, 16, v202
	v_and_b32_e32 v177, 0xffff0000, v202
	v_lshlrev_b32_e32 v216, 16, v204
	v_and_b32_e32 v217, 0xffff0000, v204
	v_lshlrev_b32_e32 v214, 16, v186
	v_and_b32_e32 v215, 0xffff0000, v186
	v_mul_f32_e32 v8, v8, v138
	v_add_f32_e32 v16, 1.0, v16
	v_add_f32_e32 v186, 1.0, v12
	v_add_f32_e32 v17, 1.0, v17
	v_rcp_f32_e32 v12, v178
	v_rcp_f32_e32 v11, v179
	v_pk_fma_f32 v[178:179], v[2:3], v[176:177], v[148:149]
	v_pk_fma_f32 v[176:177], v[6:7], v[216:217], v[174:175]
	v_add_f32_e32 v2, 1.0, v182
	v_mul_f32_e32 v6, v9, v138
	v_exp_f32_e32 v8, v8
	v_rcp_f32_e32 v10, v14
	v_rcp_f32_e32 v14, v16
	v_rcp_f32_e32 v16, v186
	v_rcp_f32_e32 v15, v17
	v_rcp_f32_e32 v17, v2
	v_exp_f32_e32 v9, v6
	v_lshlrev_b32_e32 v2, 16, v183
	v_and_b32_e32 v3, 0xffff0000, v183
	v_lshlrev_b32_e32 v6, 16, v205
	v_and_b32_e32 v7, 0xffff0000, v205
	v_mul_f32_e32 v4, v4, v138
	v_add_f32_e32 v8, 1.0, v8
	v_pk_fma_f32 v[182:183], v[16:17], v[6:7], v[2:3]
	v_add_f32_e32 v2, 1.0, v9
	v_mul_f32_e32 v5, v5, v138
	v_exp_f32_e32 v4, v4
	v_rcp_f32_e32 v8, v8
	v_rcp_f32_e32 v9, v2
	v_exp_f32_e32 v5, v5
	v_lshlrev_b32_e32 v2, 16, v185
	v_and_b32_e32 v3, 0xffff0000, v185
	v_lshlrev_b32_e32 v6, 16, v211
	v_and_b32_e32 v7, 0xffff0000, v211
	v_add_f32_e32 v4, 1.0, v4
	v_rcp_f32_e32 v13, v184
	v_pk_fma_f32 v[184:185], v[8:9], v[6:7], v[2:3]
	v_add_f32_e32 v2, 1.0, v5
	v_rcp_f32_e32 v4, v4
	v_rcp_f32_e32 v5, v2
	v_lshlrev_b32_e32 v180, 16, v181
	v_and_b32_e32 v181, 0xffff0000, v181
	v_lshlrev_b32_e32 v218, 16, v210
	v_and_b32_e32 v219, 0xffff0000, v210
	v_lshlrev_b32_e32 v220, 16, v212
	v_and_b32_e32 v221, 0xffff0000, v212
	v_lshlrev_b32_e32 v202, 16, v203
	v_and_b32_e32 v203, 0xffff0000, v203
	v_lshlrev_b32_e32 v2, 16, v187
	v_and_b32_e32 v3, 0xffff0000, v187
	v_lshlrev_b32_e32 v6, 16, v213
	v_and_b32_e32 v7, 0xffff0000, v213
	v_pk_fma_f32 v[174:175], v[10:11], v[218:219], v[206:207]
	v_pk_fma_f32 v[148:149], v[12:13], v[220:221], v[214:215]
	v_pk_fma_f32 v[180:181], v[14:15], v[202:203], v[180:181]
	v_pk_fma_f32 v[186:187], v[4:5], v[6:7], v[2:3]
	v_pk_mul_f32 v[2:3], v[178:179], v[178:179]
	v_pk_mul_f32 v[4:5], v[180:181], v[180:181]
	v_pk_mul_f32 v[6:7], v[176:177], v[176:177]
	v_pk_mul_f32 v[8:9], v[182:183], v[182:183]
	v_pk_mul_f32 v[10:11], v[174:175], v[174:175]
	v_pk_mul_f32 v[12:13], v[184:185], v[184:185]
	v_pk_mul_f32 v[14:15], v[148:149], v[148:149]
	v_pk_mul_f32 v[16:17], v[186:187], v[186:187]
	v_add_f32_e32 v14, v14, v15
	v_add_f32_e32 v16, v16, v17
	v_add_f32_e32 v12, v12, v13
	v_add_f32_e32 v10, v10, v11
	v_add_f32_e32 v8, v8, v9
	v_add_f32_e32 v6, v6, v7
	v_add_f32_e32 v4, v4, v5
	v_add_f32_e32 v2, v2, v3
	v_add_f32_e32 v14, v14, v16
	v_add_f32_e32 v10, v10, v12
	v_add_f32_e32 v6, v6, v8
	v_add_f32_e32 v2, v2, v4
	v_add_f32_e32 v10, v10, v14
	v_add_f32_e32 v2, v2, v6
	v_add_f32_e32 v2, v2, v10
	ds_bpermute_b32 v3, v188, v2
	s_waitcnt lgkmcnt(0)
	v_add_f32_e32 v2, v2, v3
	ds_bpermute_b32 v3, v189, v2
	v_lshl_add_u64 v[188:189], v[170:171], 2, s[14:15]
	s_and_saveexec_b64 s[0:1], vcc
	s_cbranch_execz .LBB0_1466
	s_waitcnt lgkmcnt(0)
	v_add_f32_e32 v2, v2, v3
	flat_atomic_add_f32 v[188:189], v2
	flat_atomic_add_f32 v[146:147], v224
	flat_atomic_add_f32 v[152:153], v225
	flat_atomic_add_f32 v[156:157], v226
	flat_atomic_add_f32 v[160:161], v227
	flat_atomic_add_f32 v[164:165], v228
	flat_atomic_add_f32 v[168:169], v229
	flat_atomic_add_f32 v[172:173], v230
